# stack: DMA scan v2 + prep load reorder + up-GEMM epilogue: taps via LDS-DMA before the K-loop, row-scale slots prefetched (no loads at epilogue start)
# baseline (speedup 1.0000x reference)
; #define PG8_LAS __attribute__((address_space(3)))
; template <class Epi, class Sched, bool ALIGN_EPI = false, bool SP2 = false>
; __device__ __forceinline__ void gemm_phase(PG8_LAS unsigned char* lds, const Gemm g, const Sched& S, const Epi& E) {
;     ...
;     for (;;) {
;         const bool has_next = S.next(ui + 1, nxt);
;         const char* nA = has_next ? (const char*)g.A + (size_t)nxt.pm * tstep : cA; const char* nB = has_next ? (const char*)g.Bt + (size_t)nxt.pn * tstep : cB;
;         for (int t = 0; t < nt; t += 2) {
;             const bool last = (t == nt - 2);
;             const char* a1 = cA + (size_t)(t + 1) * kstep;
;             const char* a2 = last ? nA : cA + (size_t)(t + 2) * kstep; const char* b2 = last ? nB : cB + (size_t)(t + 2) * kstep;
;             const char* a3 = a2 + kstep; const char* b3 = b2 + kstep;
;     __device__ __forceinline__ void operator()(f32x4 (&acc)[2][2][4][2], const pg8::Unit& u, int wr, int wc, int fr, int fq) const {
;         const int colj = u.pn * 128 + wc * 32 + 8 * fq;
;         PG8_LAS unsigned char* wl = WL + (wr * 4 + wc) * 1024;
;         {
;             const int l = fq * 16 + fr, p = l >> 4, bj = (l >> 3) & 1, c4 = (l & 7) * 4;
;             const float* srcp = (p < 3 ? FW + p * NUP : FB) + bj * DFF + u.pn * 128 + wc * 32 + c4;
;             *(PG8_LAS f32x4*)(wl + l * 16) = *(const f32x4*)srcp;
.LBB0_744:
	s_ashr_i32 s43, s42, 31
	s_lshl_b64 s[12:13], s[42:43], 19
	s_add_u32 s44, s2, s12
	s_addc_u32 s45, s3, s13
	s_and_b64 s[12:13], s[4:5], exec
	s_cselect_b32 s43, s45, s9
	s_cselect_b32 s67, s44, s8
	s_ashr_i32 s41, s40, 31
	s_lshl_b64 s[12:13], s[40:41], 19
	s_add_u32 s46, s18, s12
	s_addc_u32 s47, s19, s13
	s_and_b64 s[12:13], s[4:5], exec
	s_cselect_b32 s41, s47, s11
	s_cselect_b32 s68, s46, s10
	s_add_u32 s69, s10, 0x100
	v_mov_b32_e32 v80, 0
	s_addc_u32 s70, s11, 0
	s_mov_b32 s71, -2
	v_mov_b32_e32 v81, v80
	v_mov_b32_e32 v82, v80
	v_mov_b32_e32 v83, v80
	v_mov_b32_e32 v84, v80
	v_mov_b32_e32 v85, v80
	v_mov_b32_e32 v86, v80
	v_mov_b32_e32 v87, v80
	v_mov_b32_e32 v64, v80
	v_mov_b32_e32 v65, v80
	v_mov_b32_e32 v66, v80
	v_mov_b32_e32 v67, v80
	v_mov_b32_e32 v68, v80
	v_mov_b32_e32 v69, v80
	v_mov_b32_e32 v70, v80
	v_mov_b32_e32 v71, v80
	v_mov_b32_e32 v72, v80
	v_mov_b32_e32 v73, v80
	v_mov_b32_e32 v74, v80
	v_mov_b32_e32 v75, v80
	v_mov_b32_e32 v76, v80
	v_mov_b32_e32 v77, v80
	v_mov_b32_e32 v78, v80
	v_mov_b32_e32 v79, v80
	v_mov_b32_e32 v16, v80
	v_mov_b32_e32 v17, v80
	v_mov_b32_e32 v18, v80
	v_mov_b32_e32 v19, v80
	v_mov_b32_e32 v20, v80
	v_mov_b32_e32 v21, v80
	v_mov_b32_e32 v22, v80
	v_mov_b32_e32 v23, v80
	v_mov_b32_e32 v24, v80
	v_mov_b32_e32 v25, v80
	v_mov_b32_e32 v26, v80
	v_mov_b32_e32 v27, v80
	v_mov_b32_e32 v28, v80
	v_mov_b32_e32 v29, v80
	v_mov_b32_e32 v30, v80
	v_mov_b32_e32 v31, v80
	v_mov_b32_e32 v0, v80
	v_mov_b32_e32 v1, v80
	v_mov_b32_e32 v2, v80
	v_mov_b32_e32 v3, v80
	v_mov_b32_e32 v4, v80
	v_mov_b32_e32 v5, v80
	v_mov_b32_e32 v6, v80
	v_mov_b32_e32 v7, v80
	v_mov_b32_e32 v8, v80
	v_mov_b32_e32 v9, v80
	v_mov_b32_e32 v10, v80
	v_mov_b32_e32 v11, v80
	v_mov_b32_e32 v12, v80
	v_mov_b32_e32 v13, v80
	v_mov_b32_e32 v14, v80
	v_mov_b32_e32 v15, v80
	v_mov_b32_e32 v32, v80
	v_mov_b32_e32 v33, v80
	v_mov_b32_e32 v34, v80
	v_mov_b32_e32 v35, v80
	v_mov_b32_e32 v36, v80
	v_mov_b32_e32 v37, v80
	v_mov_b32_e32 v38, v80
	v_mov_b32_e32 v39, v80
	v_mov_b32_e32 v40, v80
	v_mov_b32_e32 v41, v80
	v_mov_b32_e32 v42, v80
	v_mov_b32_e32 v43, v80
	v_mov_b32_e32 v44, v80
	v_mov_b32_e32 v45, v80
	v_mov_b32_e32 v46, v80
	v_mov_b32_e32 v47, v80
	v_mov_b32_e32 v48, v80
	v_mov_b32_e32 v49, v80
	v_mov_b32_e32 v50, v80
	v_mov_b32_e32 v51, v80
	v_mov_b32_e32 v52, v80
	v_mov_b32_e32 v53, v80
	v_mov_b32_e32 v54, v80
	v_mov_b32_e32 v55, v80
	v_mov_b32_e32 v56, v80
	v_mov_b32_e32 v57, v80
	v_mov_b32_e32 v58, v80
	v_mov_b32_e32 v59, v80
	v_mov_b32_e32 v60, v80
	v_mov_b32_e32 v61, v80
	v_mov_b32_e32 v62, v80
	v_mov_b32_e32 v63, v80
	v_mov_b32_e32 v96, v80
	v_mov_b32_e32 v97, v80
	v_mov_b32_e32 v98, v80
	v_mov_b32_e32 v99, v80
	v_mov_b32_e32 v100, v80
	v_mov_b32_e32 v101, v80
	v_mov_b32_e32 v102, v80
	v_mov_b32_e32 v103, v80
	v_mov_b32_e32 v104, v80
	v_mov_b32_e32 v105, v80
	v_mov_b32_e32 v106, v80
	v_mov_b32_e32 v107, v80
	v_mov_b32_e32 v108, v80
	v_mov_b32_e32 v109, v80
	v_mov_b32_e32 v110, v80
	v_mov_b32_e32 v111, v80
	v_mov_b32_e32 v112, v80
	v_mov_b32_e32 v113, v80
	v_mov_b32_e32 v114, v80
	v_mov_b32_e32 v115, v80
	v_mov_b32_e32 v88, v80
	v_mov_b32_e32 v89, v80
	v_mov_b32_e32 v90, v80
	v_mov_b32_e32 v91, v80
	v_mov_b32_e32 v116, v80
	v_mov_b32_e32 v117, v80
	v_mov_b32_e32 v118, v80
	v_mov_b32_e32 v119, v80
	v_mov_b32_e32 v120, v80
	v_mov_b32_e32 v121, v80
	v_mov_b32_e32 v122, v80
	v_mov_b32_e32 v123, v80
	v_mov_b32_e32 v92, v80
	v_mov_b32_e32 v93, v80
	v_mov_b32_e32 v94, v80
	v_mov_b32_e32 v95, v80
	v_mov_b32_e32 v124, v80
	v_mov_b32_e32 v125, v80
	v_mov_b32_e32 v126, v80
	v_mov_b32_e32 v127, v80
	s_lshl_b32 s86, s66, 7
	s_ashr_i32 s87, s86, 31
	v_readfirstlane_b32 s88, v152
	v_lshl_add_u64 v[238:239], s[86:87], 2, v[136:137]
	s_lshr_b32 s88, s88, 6
	s_lshl_b32 s88, s88, 10
	s_add_i32 s88, s88, 0x20100
	s_mov_b32 m0, s88
	s_nop 0
	global_load_lds_dwordx4 v[238:239], off
.LBB0_745:
	s_cmp_eq_u32 s71, 12
	s_cbranch_scc0 .Lg3_nopf
	v_lshl_add_u32 v254, s34, 8, v187
	v_mov_b32_e32 v255, 0
	v_lshlrev_b32_e32 v254, 6, v254
	v_lshl_add_u64 v[250:251], v[254:255], 0, v[138:139]
	global_load_dwordx4 v[238:241], v[250:251], off
	global_load_dwordx4 v[242:245], v[250:251], off offset:64
	global_load_dwordx4 v[246:249], v[250:251], off offset:128
	global_load_dwordx2 v[254:255], v[250:251], off offset:192
	global_load_dwordx2 v[250:251], v[250:251], off offset:200

; #define PG8_LAS __attribute__((address_space(3)))
;     __device__ __forceinline__ void operator()(f32x4 (&acc)[2][2][4][2], const pg8::Unit& u, int wr, int wc, int fr, int fq) const {
;     ...
;         for (int ai = 0; ai < 2; ++ai) {
;             const int tb = u.pm * 256 + ai * 128 + wr * 64 + 4 * fr;
;             float rstd[4];
; #pragma unroll
;             for (int m = 0; m < 4; ++m) { const f32x4 sv = *(const f32x4*)(SS + (size_t)(tb + m) * 16 + 4 * fq); float s = (sv[0] + sv[1]) + (sv[2] + sv[3]); s += __shfl_xor(s, 16); s += __shfl_xor(s, 32);
;                 rstd[m] = rsqrtf(s * (1.0f / 1024.0f) + EPS); }
;             u32x2 pk[2][4];
; #pragma unroll
;             for (int n = 0; n < 2; ++n) {
;                 f32x4 g[4];
;                 {   const PG8_LAS unsigned char* wq = wl + (8 * fq + 4 * n) * 4;
;                     const f32x4 w0 = *(const PG8_LAS f32x4*)(wq), w1 = *(const PG8_LAS f32x4*)(wq + 256), w2 = *(const PG8_LAS f32x4*)(wq + 512), bb = *(const PG8_LAS f32x4*)(wq + 768);
;                     const f32x4 x0 = acc[ai][0][0][n] * rstd[0], x1 = acc[ai][0][1][n] * rstd[1], x2 = acc[ai][0][2][n] * rstd[2], x3 = acc[ai][0][3][n] * rstd[3];
.LBB0_748:
	v_lshl_add_u32 v148, s34, 8, v187
	v_or_b32_e32 v150, 1, v148
	v_or_b32_e32 v154, 2, v148
	v_or_b32_e32 v156, 3, v148
	s_lshl_b32 s8, s66, 7
	s_ashr_i32 s9, s8, 31
	v_and_b32_e32 v151, 64, v194
	v_xor_b32_e32 v149, 16, v194
	v_add_u32_e32 v151, 64, v151
	v_cmp_lt_i32_e32 vcc, v149, v151
	v_xor_b32_e32 v155, 32, v194
	v_mov_b64_e32 v[184:185], s[38:39]
	v_cndmask_b32_e32 v149, v194, v149, vcc
	v_lshlrev_b32_e32 v149, 2, v149
	v_cmp_lt_i32_e32 vcc, v155, v151
	v_or_b32_e32 v158, s8, v186
	v_ashrrev_i32_e32 v159, 31, v158
	v_cndmask_b32_e32 v151, v194, v155, vcc
	v_lshlrev_b32_e32 v151, 2, v151
	s_waitcnt vmcnt(16)
	v_mov_b32_e32 v160, v238
	v_mov_b32_e32 v161, v239
	v_mov_b32_e32 v162, v240
	v_mov_b32_e32 v163, v241
	v_mov_b32_e32 v164, v242
	v_mov_b32_e32 v165, v243
	v_mov_b32_e32 v166, v244
	v_mov_b32_e32 v167, v245
	v_mov_b32_e32 v172, v246
	v_mov_b32_e32 v173, v247
	v_mov_b32_e32 v174, v248
	v_mov_b32_e32 v175, v249
	v_mov_b32_e32 v176, v254
	v_mov_b32_e32 v177, v255
	v_mov_b32_e32 v178, v250
	v_mov_b32_e32 v179, v251
	v_add_u32_e32 v250, 0x80, v148
	v_ashrrev_i32_e32 v251, 31, v250
	v_lshlrev_b64 v[246:247], 6, v[250:251]
	v_lshl_add_u64 v[246:247], v[138:139], 0, v[246:247]
	global_load_dwordx4 v[230:233], v[246:247], off
	v_add_u32_e32 v250, 0x81, v148
	v_ashrrev_i32_e32 v251, 31, v250
	v_lshlrev_b64 v[246:247], 6, v[250:251]
	v_lshl_add_u64 v[246:247], v[138:139], 0, v[246:247]
	global_load_dwordx4 v[234:237], v[246:247], off
	v_add_u32_e32 v250, 0x82, v148
	v_ashrrev_i32_e32 v251, 31, v250
	v_lshlrev_b64 v[246:247], 6, v[250:251]
	v_lshl_add_u64 v[246:247], v[138:139], 0, v[246:247]
	global_load_dwordx4 v[238:241], v[246:247], off
	v_add_u32_e32 v250, 0x83, v148
	v_ashrrev_i32_e32 v251, 31, v250
	v_lshlrev_b64 v[246:247], 6, v[250:251]
	v_lshl_add_u64 v[246:247], v[138:139], 0, v[246:247]
	global_load_dwordx4 v[242:245], v[246:247], off
	v_mov_b32_e32 v196, v161
	v_mov_b32_e32 v197, v162
	v_mov_b32_e32 v161, v163
	v_mov_b32_e32 v162, v165
	v_mov_b32_e32 v163, v166
	v_mov_b32_e32 v165, v167
	v_mov_b32_e32 v166, v173
	v_mov_b32_e32 v167, v174
	v_mov_b32_e32 v173, v175
	v_pk_add_f32 v[160:161], v[196:197], v[160:161]
	v_pk_add_f32 v[162:163], v[162:163], v[164:165]
	v_mov_b32_e32 v174, v177
	v_mov_b32_e32 v175, v178
	v_mov_b32_e32 v177, v179
	v_pk_add_f32 v[166:167], v[166:167], v[172:173]
	v_pk_add_f32 v[172:173], v[174:175], v[176:177]
	v_mov_b32_e32 v165, v160
	v_mov_b32_e32 v164, v162
	v_mov_b32_e32 v160, v163
	v_mov_b32_e32 v162, v172
	v_mov_b32_e32 v163, v166
	v_mov_b32_e32 v166, v173
	v_pk_add_f32 v[160:161], v[164:165], v[160:161]
	v_pk_add_f32 v[162:163], v[162:163], v[166:167]
	ds_bpermute_b32 v165, v149, v161
	ds_bpermute_b32 v164, v149, v160
	ds_bpermute_b32 v167, v149, v163
	ds_bpermute_b32 v166, v149, v162
	s_waitcnt lgkmcnt(2)
	v_pk_add_f32 v[172:173], v[160:161], v[164:165]
	ds_bpermute_b32 v197, v151, v173
	s_waitcnt lgkmcnt(1)
	v_pk_add_f32 v[174:175], v[162:163], v[166:167]
	ds_bpermute_b32 v196, v151, v172
	ds_bpermute_b32 v199, v151, v175
	ds_bpermute_b32 v198, v151, v174
	ds_read_b128 v[160:163], v195
	ds_read_b128 v[164:167], v195 offset:256
	ds_read_b128 v[176:179], v195 offset:512
	ds_read_b128 v[180:183], v195 offset:768
	s_waitcnt lgkmcnt(6)
	v_pk_add_f32 v[172:173], v[172:173], v[196:197]
	s_nop 0
	v_pk_fma_f32 v[172:173], v[172:173], s[24:25], v[184:185] op_sel_hi:[1,0,0]
	s_waitcnt lgkmcnt(4)
	v_pk_add_f32 v[174:175], v[174:175], v[198:199]
	v_mul_f32_e32 v155, 0x4b800000, v173
	v_pk_fma_f32 v[174:175], v[174:175], s[24:25], v[184:185] op_sel_hi:[1,0,0]
	v_cmp_gt_f32_e32 vcc, s63, v173
	v_mul_f32_e32 v168, 0x4b800000, v175
	v_mul_f32_e32 v170, 0x4b800000, v174
	v_cmp_gt_f32_e64 s[10:11], s63, v175
	v_cmp_gt_f32_e64 s[12:13], s63, v174
	v_cndmask_b32_e32 v155, v173, v155, vcc
	v_cndmask_b32_e64 v168, v175, v168, s[10:11]
	v_cndmask_b32_e64 v170, v174, v170, s[12:13]
	v_rsq_f32_e32 v155, v155
	v_rsq_f32_e32 v168, v168
	v_rsq_f32_e32 v173, v170
	v_mul_f32_e32 v157, 0x4b800000, v172
	v_cmp_gt_f32_e64 s[8:9], s63, v172
	v_mul_f32_e32 v170, 0x45800000, v155
	v_mul_f32_e32 v175, 0x45800000, v168
	v_cndmask_b32_e64 v157, v172, v157, s[8:9]
	v_mul_f32_e32 v184, 0x45800000, v173
	v_rsq_f32_e32 v157, v157
	v_cndmask_b32_e32 v174, v155, v170, vcc
	v_cndmask_b32_e64 v170, v168, v175, s[10:11]
	v_cndmask_b32_e64 v168, v173, v184, s[12:13]
	v_pk_mul_f32 v[124:125], v[124:125], v[174:175] op_sel_hi:[1,0]
	v_pk_mul_f32 v[112:113], v[112:113], v[168:169] op_sel_hi:[1,0]
	v_pk_mul_f32 v[116:117], v[116:117], v[170:171] op_sel_hi:[1,0]
	s_waitcnt lgkmcnt(0)
; #define PG8_LAS __attribute__((address_space(3)))
; __device__ __forceinline__ float row_up1(float v) { return dpp_mov<0x111>(v); }
; __device__ __forceinline__ float siluf_(float x) { return x * __builtin_amdgcn_rcpf(1.0f + __builtin_amdgcn_exp2f(x * -1.4426950408889634f)); }
;     __device__ __forceinline__ void operator()(f32x4 (&acc)[2][2][4][2], const pg8::Unit& u, int wr, int wc, int fr, int fq) const {
;     ...
;                 {   const PG8_LAS unsigned char* wq = wl + (8 * fq + 4 * n) * 4;
;                     const f32x4 w0 = *(const PG8_LAS f32x4*)(wq), w1 = *(const PG8_LAS f32x4*)(wq + 256), w2 = *(const PG8_LAS f32x4*)(wq + 512), bb = *(const PG8_LAS f32x4*)(wq + 768);
;                     const f32x4 x0 = acc[ai][0][0][n] * rstd[0], x1 = acc[ai][0][1][n] * rstd[1], x2 = acc[ai][0][2][n] * rstd[2], x3 = acc[ai][0][3][n] * rstd[3];
;                     acc[ai][0][0][n] = x0; acc[ai][0][1][n] = x1; acc[ai][0][2][n] = x2; acc[ai][0][3][n] = x3;
;                     f32x4 p1, p2;
; #pragma unroll
;                     for (int c = 0; c < 4; ++c) { p1[c] = row_up1(x3[c]); p2[c] = row_up1(x2[c]); }
;                     g[0] = bb + w2 * x0 + w1 * p1 + w0 * p2; g[1] = bb + w2 * x1 + w1 * x0 + w0 * p1;
;                     g[2] = bb + w2 * x2 + w1 * x1 + w0 * x0; g[3] = bb + w2 * x3 + w1 * x2 + w0 * x1;
; #pragma unroll
;                     for (int m = 0; m < 4; ++m)
; #pragma unroll
;                         for (int c = 0; c < 4; ++c) g[m][c] = siluf_(g[m][c]);
;                 }
;                 __builtin_amdgcn_sched_barrier(0);
;                 {   const PG8_LAS unsigned char* wq = wl + 128 + (8 * fq + 4 * n) * 4;
;                     const f32x4 w0 = *(const PG8_LAS f32x4*)(wq), w1 = *(const PG8_LAS f32x4*)(wq + 256), w2 = *(const PG8_LAS f32x4*)(wq + 512), bb = *(const PG8_LAS f32x4*)(wq + 768);
	v_pk_fma_f32 v[204:205], v[176:177], v[124:125], v[180:181]
	v_mov_b32_dpp v184, v112 row_shr:1 row_mask:0xf bank_mask:0xf bound_ctrl:1
	v_mov_b32_dpp v185, v113 row_shr:1 row_mask:0xf bank_mask:0xf bound_ctrl:1
	v_mov_b32_dpp v196, v116 row_shr:1 row_mask:0xf bank_mask:0xf bound_ctrl:1
	v_mov_b32_dpp v197, v117 row_shr:1 row_mask:0xf bank_mask:0xf bound_ctrl:1
	v_pk_fma_f32 v[204:205], v[164:165], v[184:185], v[204:205]
	v_mul_f32_e32 v172, 0x45800000, v157
	v_pk_fma_f32 v[196:197], v[160:161], v[196:197], v[204:205]
	v_cndmask_b32_e64 v172, v157, v172, s[8:9]
	v_mul_f32_e32 v155, 0xbfb8aa3b, v196
	v_pk_mul_f32 v[126:127], v[126:127], v[174:175] op_sel_hi:[1,0]
	v_pk_mul_f32 v[120:121], v[120:121], v[172:173] op_sel_hi:[1,0]
	v_pk_mul_f32 v[114:115], v[114:115], v[168:169] op_sel_hi:[1,0]
	v_exp_f32_e32 v155, v155
	v_mul_f32_e32 v157, 0xbfb8aa3b, v197
	v_pk_mul_f32 v[118:119], v[118:119], v[170:171] op_sel_hi:[1,0]
	v_mov_b32_dpp v198, v114 row_shr:1 row_mask:0xf bank_mask:0xf bound_ctrl:1
	v_mov_b32_dpp v199, v115 row_shr:1 row_mask:0xf bank_mask:0xf bound_ctrl:1
	v_pk_fma_f32 v[202:203], v[178:179], v[126:127], v[182:183]
	v_pk_fma_f32 v[204:205], v[176:177], v[120:121], v[180:181]
	v_exp_f32_e32 v157, v157
	v_pk_mul_f32 v[122:123], v[122:123], v[172:173] op_sel_hi:[1,0]
	v_mov_b32_dpp v200, v118 row_shr:1 row_mask:0xf bank_mask:0xf bound_ctrl:1
	v_mov_b32_dpp v201, v119 row_shr:1 row_mask:0xf bank_mask:0xf bound_ctrl:1
	v_pk_fma_f32 v[202:203], v[166:167], v[198:199], v[202:203]
	v_pk_fma_f32 v[204:205], v[164:165], v[124:125], v[204:205]
	v_pk_fma_f32 v[200:201], v[162:163], v[200:201], v[202:203]
	v_pk_fma_f32 v[202:203], v[178:179], v[122:123], v[182:183]
	v_pk_fma_f32 v[184:185], v[160:161], v[184:185], v[204:205]
	v_pk_fma_f32 v[204:205], v[176:177], v[116:117], v[180:181]
	v_pk_fma_f32 v[176:177], v[176:177], v[112:113], v[180:181]
	v_pk_fma_f32 v[202:203], v[166:167], v[126:127], v[202:203]
	v_pk_fma_f32 v[204:205], v[164:165], v[120:121], v[204:205]
	v_pk_fma_f32 v[164:165], v[164:165], v[116:117], v[176:177]
	v_add_f32_e32 v155, 1.0, v155
	v_pk_fma_f32 v[198:199], v[162:163], v[198:199], v[202:203]
	v_pk_fma_f32 v[202:203], v[178:179], v[118:119], v[182:183]
	v_pk_fma_f32 v[204:205], v[160:161], v[124:125], v[204:205]
	v_pk_fma_f32 v[178:179], v[178:179], v[114:115], v[182:183]
	v_pk_fma_f32 v[214:215], v[160:161], v[120:121], v[164:165]
	v_rcp_f32_e32 v160, v155
	v_add_f32_e32 v155, 1.0, v157
	v_mul_f32_e32 v157, 0xbfb8aa3b, v200
	v_pk_fma_f32 v[202:203], v[166:167], v[122:123], v[202:203]
	v_pk_fma_f32 v[166:167], v[166:167], v[118:119], v[178:179]
	v_exp_f32_e32 v157, v157
	v_mul_f32_e32 v161, 0xbfb8aa3b, v201
	v_pk_fma_f32 v[202:203], v[162:163], v[126:127], v[202:203]
	v_pk_fma_f32 v[212:213], v[162:163], v[122:123], v[166:167]
	v_exp_f32_e32 v163, v161
	v_rcp_f32_e32 v161, v155
	v_add_f32_e32 v155, 1.0, v157
	v_rcp_f32_e32 v162, v155
	v_add_f32_e32 v155, 1.0, v163
	v_rcp_f32_e32 v163, v155
	v_mul_f32_e32 v155, 0xbfb8aa3b, v184
	v_exp_f32_e32 v155, v155
	v_mul_f32_e32 v157, 0xbfb8aa3b, v185
	v_exp_f32_e32 v157, v157
	v_pk_mul_f32 v[216:217], v[196:197], v[160:161]
	v_add_f32_e32 v155, 1.0, v155
	v_rcp_f32_e32 v160, v155
	v_add_f32_e32 v155, 1.0, v157
	v_mul_f32_e32 v157, 0xbfb8aa3b, v198
	v_exp_f32_e32 v157, v157
	v_mul_f32_e32 v161, 0xbfb8aa3b, v199
	v_pk_mul_f32 v[218:219], v[200:201], v[162:163]
	v_exp_f32_e32 v163, v161
	v_rcp_f32_e32 v161, v155
	v_add_f32_e32 v155, 1.0, v157
	v_rcp_f32_e32 v162, v155
	v_add_f32_e32 v155, 1.0, v163
	v_rcp_f32_e32 v163, v155
	v_mul_f32_e32 v155, 0xbfb8aa3b, v204
	v_exp_f32_e32 v155, v155
	v_mul_f32_e32 v157, 0xbfb8aa3b, v205
	v_exp_f32_e32 v157, v157
	v_pk_mul_f32 v[184:185], v[184:185], v[160:161]
	v_add_f32_e32 v155, 1.0, v155
	v_rcp_f32_e32 v160, v155
	v_add_f32_e32 v155, 1.0, v157
	v_mul_f32_e32 v157, 0xbfb8aa3b, v202
	v_exp_f32_e32 v157, v157
	v_mul_f32_e32 v161, 0xbfb8aa3b, v203
	v_exp_f32_e32 v165, v161
	v_rcp_f32_e32 v161, v155
	v_add_f32_e32 v155, 1.0, v157
	v_mul_f32_e32 v157, 0xbfb8aa3b, v214
	v_rcp_f32_e32 v164, v155
	v_add_f32_e32 v155, 1.0, v165
	v_exp_f32_e32 v157, v157
	v_mul_f32_e32 v165, 0xbfb8aa3b, v215
	v_exp_f32_e32 v166, v165
	v_rcp_f32_e32 v165, v155
	v_add_f32_e32 v155, 1.0, v157
	v_mul_f32_e32 v157, 0xbfb8aa3b, v212
	v_rcp_f32_e32 v220, v155
	v_add_f32_e32 v155, 1.0, v166
	v_exp_f32_e32 v157, v157
	v_mul_f32_e32 v166, 0xbfb8aa3b, v213
	v_exp_f32_e32 v166, v166
	v_rcp_f32_e32 v221, v155
	v_add_f32_e32 v155, 1.0, v157
	v_rcp_f32_e32 v222, v155
	v_add_f32_e32 v155, 1.0, v166
	v_rcp_f32_e32 v223, v155
	v_pk_mul_f32 v[224:225], v[198:199], v[162:163]
	v_pk_mul_f32 v[226:227], v[204:205], v[160:161]
	v_pk_mul_f32 v[228:229], v[202:203], v[164:165]
	ds_read_b128 v[196:199], v195 offset:128
	ds_read_b128 v[200:203], v195 offset:384
	ds_read_b128 v[204:207], v195 offset:640
	ds_read_b128 v[208:211], v195 offset:896
	v_pk_mul_f32 v[176:177], v[108:109], v[174:175] op_sel_hi:[1,0]
	v_pk_mul_f32 v[164:165], v[96:97], v[168:169] op_sel_hi:[1,0]
	v_pk_mul_f32 v[180:181], v[100:101], v[170:171] op_sel_hi:[1,0]
	v_pk_mul_f32 v[160:161], v[104:105], v[172:173] op_sel_hi:[1,0]
	v_mov_b32_dpp v96, v164 row_shr:1 row_mask:0xf bank_mask:0xf bound_ctrl:1
	v_mov_b32_dpp v97, v165 row_shr:1 row_mask:0xf bank_mask:0xf bound_ctrl:1
	s_waitcnt lgkmcnt(0)
;     __device__ __forceinline__ void operator()(f32x4 (&acc)[2][2][4][2], const pg8::Unit& u, int wr, int wc, int fr, int fq) const {
;     ...
;                 {   const PG8_LAS unsigned char* wq = wl + (8 * fq + 4 * n) * 4;
;                     const f32x4 w0 = *(const PG8_LAS f32x4*)(wq), w1 = *(const PG8_LAS f32x4*)(wq + 256), w2 = *(const PG8_LAS f32x4*)(wq + 512), bb = *(const PG8_LAS f32x4*)(wq + 768);
;                     const f32x4 x0 = acc[ai][0][0][n] * rstd[0], x1 = acc[ai][0][1][n] * rstd[1], x2 = acc[ai][0][2][n] * rstd[2], x3 = acc[ai][0][3][n] * rstd[3];
;                     acc[ai][0][0][n] = x0; acc[ai][0][1][n] = x1; acc[ai][0][2][n] = x2; acc[ai][0][3][n] = x3;
;                     f32x4 p1, p2;
; #pragma unroll
;                     for (int c = 0; c < 4; ++c) { p1[c] = row_up1(x3[c]); p2[c] = row_up1(x2[c]); }
;                     g[0] = bb + w2 * x0 + w1 * p1 + w0 * p2; g[1] = bb + w2 * x1 + w1 * x0 + w0 * p1;
;                     g[2] = bb + w2 * x2 + w1 * x1 + w0 * x0; g[3] = bb + w2 * x3 + w1 * x2 + w0 * x1;
; #pragma unroll
;                     for (int m = 0; m < 4; ++m)
; #pragma unroll
;                         for (int c = 0; c < 4; ++c) g[m][c] = siluf_(g[m][c]);
;                 }
;                 __builtin_amdgcn_sched_barrier(0);
;                 {   const PG8_LAS unsigned char* wq = wl + 128 + (8 * fq + 4 * n) * 4;
;                     const f32x4 w0 = *(const PG8_LAS f32x4*)(wq), w1 = *(const PG8_LAS f32x4*)(wq + 256), w2 = *(const PG8_LAS f32x4*)(wq + 512), bb = *(const PG8_LAS f32x4*)(wq + 768);
;                     const f32x4 x0 = acc[ai][1][0][n] * rstd[0], x1 = acc[ai][1][1][n] * rstd[1], x2 = acc[ai][1][2][n] * rstd[2], x3 = acc[ai][1][3][n] * rstd[3];
;                     acc[ai][1][0][n] = x0; acc[ai][1][1][n] = x1; acc[ai][1][2][n] = x2; acc[ai][1][3][n] = x3;
;                     f32x4 p1, p2;
; #pragma unroll
;                     for (int c = 0; c < 4; ++c) { p1[c] = row_up1(x3[c]); p2[c] = row_up1(x2[c]); }
;                     g[0] *= bb + w2 * x0 + w1 * p1 + w0 * p2; g[1] *= bb + w2 * x1 + w1 * x0 + w0 * p1;
;                     g[2] *= bb + w2 * x2 + w1 * x1 + w0 * x0; g[3] *= bb + w2 * x3 + w1 * x2 + w0 * x1;
;                 }
; #pragma unroll
;                 for (int m = 0; m < 4; ++m) { pk[n][m].x = pk2(g[m][0], g[m][1]); pk[n][m].y = pk2(g[m][2], g[m][3]); }
	v_pk_fma_f32 v[108:109], v[176:177], v[204:205], v[208:209]
	v_pk_mul_f32 v[166:167], v[98:99], v[168:169] op_sel_hi:[1,0]
	v_mov_b32_dpp v98, v180 row_shr:1 row_mask:0xf bank_mask:0xf bound_ctrl:1
	v_mov_b32_dpp v99, v181 row_shr:1 row_mask:0xf bank_mask:0xf bound_ctrl:1
	v_pk_fma_f32 v[108:109], v[200:201], v[96:97], v[108:109]
	v_pk_mul_f32 v[178:179], v[110:111], v[174:175] op_sel_hi:[1,0]
	v_pk_fma_f32 v[98:99], v[196:197], v[98:99], v[108:109]
	v_pk_fma_f32 v[108:109], v[160:161], v[204:205], v[208:209]
	v_pk_mul_f32 v[182:183], v[102:103], v[170:171] op_sel_hi:[1,0]
	v_mov_b32_dpp v100, v166 row_shr:1 row_mask:0xf bank_mask:0xf bound_ctrl:1
	v_mov_b32_dpp v101, v167 row_shr:1 row_mask:0xf bank_mask:0xf bound_ctrl:1
	v_pk_fma_f32 v[110:111], v[178:179], v[206:207], v[210:211]
	v_pk_fma_f32 v[108:109], v[176:177], v[200:201], v[108:109]
	v_pk_mul_f32 v[162:163], v[106:107], v[172:173] op_sel_hi:[1,0]
	v_mov_b32_dpp v102, v182 row_shr:1 row_mask:0xf bank_mask:0xf bound_ctrl:1
	v_mov_b32_dpp v103, v183 row_shr:1 row_mask:0xf bank_mask:0xf bound_ctrl:1
	v_pk_fma_f32 v[110:111], v[202:203], v[100:101], v[110:111]
	v_pk_fma_f32 v[96:97], v[196:197], v[96:97], v[108:109]
	v_pk_fma_f32 v[108:109], v[180:181], v[204:205], v[208:209]
	v_pk_fma_f32 v[102:103], v[198:199], v[102:103], v[110:111]
	v_pk_fma_f32 v[110:111], v[162:163], v[206:207], v[210:211]
	v_pk_fma_f32 v[108:109], v[160:161], v[200:201], v[108:109]
	v_pk_fma_f32 v[110:111], v[178:179], v[202:203], v[110:111]
	v_pk_fma_f32 v[108:109], v[176:177], v[196:197], v[108:109]
	v_pk_fma_f32 v[100:101], v[198:199], v[100:101], v[110:111]
	v_pk_mul_f32 v[96:97], v[184:185], v[96:97]
	v_pk_fma_f32 v[110:111], v[182:183], v[206:207], v[210:211]
	v_pk_mul_f32 v[184:185], v[108:109], v[226:227]
	v_pk_fma_f32 v[108:109], v[164:165], v[204:205], v[208:209]
	v_pk_fma_f32 v[204:205], v[166:167], v[206:207], v[210:211]
	v_pk_fma_f32 v[110:111], v[162:163], v[202:203], v[110:111]
	v_pk_fma_f32 v[202:203], v[182:183], v[202:203], v[204:205]
	v_pk_fma_f32 v[108:109], v[180:181], v[200:201], v[108:109]
	v_pk_mul_f32 v[106:107], v[212:213], v[222:223]
	v_pk_fma_f32 v[110:111], v[178:179], v[198:199], v[110:111]
	v_pk_fma_f32 v[108:109], v[160:161], v[196:197], v[108:109]
	v_pk_fma_f32 v[196:197], v[162:163], v[198:199], v[202:203]
	v_pk_mul_f32 v[104:105], v[214:215], v[220:221]
	v_pk_mul_f32 v[102:103], v[218:219], v[102:103]
	v_pk_mul_f32 v[98:99], v[216:217], v[98:99]
	v_pk_mul_f32 v[100:101], v[224:225], v[100:101]
	v_pk_mul_f32 v[110:111], v[110:111], v[228:229]
	v_pk_mul_f32 v[106:107], v[196:197], v[106:107]
	v_pk_mul_f32 v[196:197], v[108:109], v[104:105]
	v_cvt_pk_bf16_f32 v108, v98, v99
	v_cvt_pk_bf16_f32 v109, v102, v103
	v_cvt_pk_bf16_f32 v104, v96, v97
	v_cvt_pk_bf16_f32 v105, v100, v101
	v_cvt_pk_bf16_f32 v100, v184, v185
	v_cvt_pk_bf16_f32 v101, v110, v111
	s_nop 0
	v_cvt_pk_bf16_f32 v96, v196, v197
	v_cvt_pk_bf16_f32 v97, v106, v107
	ds_read_b128 v[196:199], v195 offset:16
	ds_read_b128 v[200:203], v195 offset:272
	ds_read_b128 v[204:207], v195 offset:528
	ds_read_b128 v[208:211], v195 offset:784
	v_pk_mul_f32 v[92:93], v[92:93], v[174:175] op_sel_hi:[1,0]
	v_pk_mul_f32 v[84:85], v[84:85], v[168:169] op_sel_hi:[1,0]
	v_pk_mul_f32 v[88:89], v[88:89], v[170:171] op_sel_hi:[1,0]
	v_pk_mul_f32 v[80:81], v[80:81], v[172:173] op_sel_hi:[1,0]
	v_mov_b32_dpp v98, v84 row_shr:1 row_mask:0xf bank_mask:0xf bound_ctrl:1
	v_mov_b32_dpp v99, v85 row_shr:1 row_mask:0xf bank_mask:0xf bound_ctrl:1
	s_waitcnt lgkmcnt(0)
	v_pk_fma_f32 v[212:213], v[92:93], v[204:205], v[208:209]
	v_mov_b32_dpp v102, v88 row_shr:1 row_mask:0xf bank_mask:0xf bound_ctrl:1
	v_mov_b32_dpp v103, v89 row_shr:1 row_mask:0xf bank_mask:0xf bound_ctrl:1
	v_pk_fma_f32 v[212:213], v[200:201], v[98:99], v[212:213]
	v_pk_mul_f32 v[94:95], v[94:95], v[174:175] op_sel_hi:[1,0]
	v_pk_fma_f32 v[102:103], v[196:197], v[102:103], v[212:213]
	v_pk_mul_f32 v[86:87], v[86:87], v[168:169] op_sel_hi:[1,0]
	v_mul_f32_e32 v155, 0xbfb8aa3b, v102
	v_exp_f32_e32 v155, v155
	v_mul_f32_e32 v157, 0xbfb8aa3b, v103
	v_pk_fma_f32 v[212:213], v[80:81], v[204:205], v[208:209]
	v_exp_f32_e32 v157, v157
	v_pk_mul_f32 v[90:91], v[90:91], v[170:171] op_sel_hi:[1,0]
	v_mov_b32_dpp v106, v86 row_shr:1 row_mask:0xf bank_mask:0xf bound_ctrl:1
	v_mov_b32_dpp v107, v87 row_shr:1 row_mask:0xf bank_mask:0xf bound_ctrl:1
	v_pk_fma_f32 v[184:185], v[94:95], v[206:207], v[210:211]
	v_pk_fma_f32 v[212:213], v[92:93], v[200:201], v[212:213]
	v_mov_b32_dpp v110, v90 row_shr:1 row_mask:0xf bank_mask:0xf bound_ctrl:1
	v_mov_b32_dpp v111, v91 row_shr:1 row_mask:0xf bank_mask:0xf bound_ctrl:1
	v_pk_fma_f32 v[184:185], v[202:203], v[106:107], v[184:185]
	v_pk_fma_f32 v[98:99], v[196:197], v[98:99], v[212:213]
	v_pk_fma_f32 v[212:213], v[88:89], v[204:205], v[208:209]
	v_pk_fma_f32 v[204:205], v[84:85], v[204:205], v[208:209]
	v_pk_fma_f32 v[110:111], v[198:199], v[110:111], v[184:185]
	v_pk_fma_f32 v[212:213], v[80:81], v[200:201], v[212:213]
	v_pk_fma_f32 v[200:201], v[88:89], v[200:201], v[204:205]
	v_add_f32_e32 v155, 1.0, v155
	v_pk_fma_f32 v[212:213], v[92:93], v[196:197], v[212:213]
	v_pk_fma_f32 v[216:217], v[80:81], v[196:197], v[200:201]
	v_rcp_f32_e32 v196, v155
	v_add_f32_e32 v155, 1.0, v157
	v_mul_f32_e32 v157, 0xbfb8aa3b, v110
	v_pk_mul_f32 v[82:83], v[82:83], v[172:173] op_sel_hi:[1,0]
	v_exp_f32_e32 v157, v157
	v_mul_f32_e32 v173, 0xbfb8aa3b, v111
	v_pk_fma_f32 v[184:185], v[82:83], v[206:207], v[210:211]
	v_exp_f32_e32 v173, v173
	v_pk_fma_f32 v[184:185], v[94:95], v[202:203], v[184:185]
	v_rcp_f32_e32 v197, v155
	v_pk_fma_f32 v[106:107], v[198:199], v[106:107], v[184:185]
; #define PG8_LAS __attribute__((address_space(3)))
; __device__ __forceinline__ unsigned pk2(float a, float b) { return pg8::cvt_pk_bf16(a, b); }
; __device__ __forceinline__ float row_up1(float v) { return dpp_mov<0x111>(v); }
;     __device__ __forceinline__ void operator()(f32x4 (&acc)[2][2][4][2], const pg8::Unit& u, int wr, int wc, int fr, int fq) const {
;     ...
;                 {   const PG8_LAS unsigned char* wq = wl + 128 + (8 * fq + 4 * n) * 4;
;                     const f32x4 w0 = *(const PG8_LAS f32x4*)(wq), w1 = *(const PG8_LAS f32x4*)(wq + 256), w2 = *(const PG8_LAS f32x4*)(wq + 512), bb = *(const PG8_LAS f32x4*)(wq + 768);
;                     const f32x4 x0 = acc[ai][1][0][n] * rstd[0], x1 = acc[ai][1][1][n] * rstd[1], x2 = acc[ai][1][2][n] * rstd[2], x3 = acc[ai][1][3][n] * rstd[3];
;                     acc[ai][1][0][n] = x0; acc[ai][1][1][n] = x1; acc[ai][1][2][n] = x2; acc[ai][1][3][n] = x3;
;                     f32x4 p1, p2;
; #pragma unroll
;                     for (int c = 0; c < 4; ++c) { p1[c] = row_up1(x3[c]); p2[c] = row_up1(x2[c]); }
;                     g[0] *= bb + w2 * x0 + w1 * p1 + w0 * p2; g[1] *= bb + w2 * x1 + w1 * x0 + w0 * p1;
;                     g[2] *= bb + w2 * x2 + w1 * x1 + w0 * x0; g[3] *= bb + w2 * x3 + w1 * x2 + w0 * x1;
;                 }
; #pragma unroll
;                 for (int m = 0; m < 4; ++m) { pk[n][m].x = pk2(g[m][0], g[m][1]); pk[n][m].y = pk2(g[m][2], g[m][3]); }
;                 __builtin_amdgcn_sched_barrier(0);
;             }
; #pragma unroll
;             for (int m = 0; m < 4; ++m) if (fr != 0 || m >= 2) {
;                 u32x4 w; w.x = pk[0][m].x; w.y = pk[0][m].y; w.z = pk[1][m].x; w.w = pk[1][m].y;
;                 *(u32x4*)(ACT + (size_t)(tb + m) * DFF + colj) = w; }
	v_pk_fma_f32 v[184:185], v[90:91], v[206:207], v[210:211]
	v_pk_fma_f32 v[206:207], v[86:87], v[206:207], v[210:211]
	v_pk_fma_f32 v[184:185], v[82:83], v[202:203], v[184:185]
	v_pk_fma_f32 v[202:203], v[90:91], v[202:203], v[206:207]
	v_add_f32_e32 v155, 1.0, v157
	v_pk_fma_f32 v[184:185], v[94:95], v[198:199], v[184:185]
	v_pk_fma_f32 v[214:215], v[82:83], v[198:199], v[202:203]
	v_rcp_f32_e32 v198, v155
	v_add_f32_e32 v155, 1.0, v173
	v_rcp_f32_e32 v199, v155
	v_mul_f32_e32 v155, 0xbfb8aa3b, v98
	v_exp_f32_e32 v155, v155
	v_mul_f32_e32 v157, 0xbfb8aa3b, v99
	v_exp_f32_e32 v157, v157
	v_pk_mul_f32 v[102:103], v[102:103], v[196:197]
	v_add_f32_e32 v155, 1.0, v155
	v_rcp_f32_e32 v196, v155
	v_add_f32_e32 v155, 1.0, v157
	v_mul_f32_e32 v157, 0xbfb8aa3b, v106
	v_exp_f32_e32 v157, v157
	v_mul_f32_e32 v173, 0xbfb8aa3b, v107
	v_exp_f32_e32 v173, v173
	v_rcp_f32_e32 v197, v155
	v_add_f32_e32 v155, 1.0, v157
	v_pk_mul_f32 v[110:111], v[110:111], v[198:199]
	v_rcp_f32_e32 v198, v155
	v_add_f32_e32 v155, 1.0, v173
	v_rcp_f32_e32 v199, v155
	v_mul_f32_e32 v155, 0xbfb8aa3b, v212
	v_exp_f32_e32 v155, v155
	v_mul_f32_e32 v157, 0xbfb8aa3b, v213
	v_exp_f32_e32 v157, v157
	v_pk_mul_f32 v[98:99], v[98:99], v[196:197]
	v_add_f32_e32 v155, 1.0, v155
	v_rcp_f32_e32 v196, v155
	v_add_f32_e32 v155, 1.0, v157
	v_mul_f32_e32 v157, 0xbfb8aa3b, v184
	v_exp_f32_e32 v157, v157
	v_mul_f32_e32 v173, 0xbfb8aa3b, v185
	v_exp_f32_e32 v173, v173
	v_rcp_f32_e32 v197, v155
	v_add_f32_e32 v155, 1.0, v157
	v_mul_f32_e32 v157, 0xbfb8aa3b, v216
	v_rcp_f32_e32 v200, v155
	v_add_f32_e32 v155, 1.0, v173
	v_exp_f32_e32 v157, v157
	v_mul_f32_e32 v173, 0xbfb8aa3b, v217
	v_exp_f32_e32 v173, v173
	v_rcp_f32_e32 v201, v155
	v_add_f32_e32 v155, 1.0, v157
	v_mul_f32_e32 v157, 0xbfb8aa3b, v214
	v_rcp_f32_e32 v218, v155
	v_add_f32_e32 v155, 1.0, v173
	v_exp_f32_e32 v157, v157
	v_mul_f32_e32 v173, 0xbfb8aa3b, v215
	v_exp_f32_e32 v173, v173
	v_rcp_f32_e32 v219, v155
	v_add_f32_e32 v155, 1.0, v157
	v_rcp_f32_e32 v220, v155
	v_add_f32_e32 v155, 1.0, v173
	v_pk_mul_f32 v[106:107], v[106:107], v[198:199]
	v_rcp_f32_e32 v221, v155
	v_pk_mul_f32 v[212:213], v[212:213], v[196:197]
	v_pk_mul_f32 v[222:223], v[184:185], v[200:201]
	ds_read_b128 v[196:199], v195 offset:144
	ds_read_b128 v[200:203], v195 offset:400
	ds_read_b128 v[204:207], v195 offset:656
	ds_read_b128 v[208:211], v195 offset:912
	v_pk_mul_f32 v[184:185], v[66:67], v[174:175] op_sel_hi:[1,0]
	v_pk_mul_f32 v[174:175], v[64:65], v[174:175] op_sel_hi:[1,0]
	v_pk_mul_f32 v[66:67], v[68:69], v[172:173] op_sel_hi:[1,0]
	v_pk_mul_f32 v[68:69], v[76:77], v[168:169] op_sel_hi:[1,0]
	v_pk_mul_f32 v[70:71], v[70:71], v[172:173] op_sel_hi:[1,0]
	v_pk_mul_f32 v[172:173], v[74:75], v[170:171] op_sel_hi:[1,0]
	v_pk_mul_f32 v[74:75], v[72:73], v[170:171] op_sel_hi:[1,0]
	v_mov_b32_dpp v64, v68 row_shr:1 row_mask:0xf bank_mask:0xf bound_ctrl:1
	v_mov_b32_dpp v65, v69 row_shr:1 row_mask:0xf bank_mask:0xf bound_ctrl:1
	v_pk_mul_f32 v[216:217], v[216:217], v[218:219]
	s_waitcnt lgkmcnt(0)
	v_pk_fma_f32 v[218:219], v[174:175], v[204:205], v[208:209]
	v_pk_mul_f32 v[72:73], v[78:79], v[168:169] op_sel_hi:[1,0]
	v_mov_b32_dpp v76, v74 row_shr:1 row_mask:0xf bank_mask:0xf bound_ctrl:1
	v_mov_b32_dpp v77, v75 row_shr:1 row_mask:0xf bank_mask:0xf bound_ctrl:1
	v_pk_fma_f32 v[218:219], v[200:201], v[64:65], v[218:219]
	v_mov_b32_dpp v78, v72 row_shr:1 row_mask:0xf bank_mask:0xf bound_ctrl:1
	v_mov_b32_dpp v79, v73 row_shr:1 row_mask:0xf bank_mask:0xf bound_ctrl:1
	v_pk_mul_f32 v[214:215], v[214:215], v[220:221]
	v_pk_fma_f32 v[220:221], v[184:185], v[206:207], v[210:211]
	v_pk_fma_f32 v[76:77], v[196:197], v[76:77], v[218:219]
	v_mov_b32_dpp v224, v172 row_shr:1 row_mask:0xf bank_mask:0xf bound_ctrl:1
	v_mov_b32_dpp v225, v173 row_shr:1 row_mask:0xf bank_mask:0xf bound_ctrl:1
	v_pk_fma_f32 v[220:221], v[202:203], v[78:79], v[220:221]
	v_pk_mul_f32 v[76:77], v[102:103], v[76:77]
	v_pk_fma_f32 v[102:103], v[66:67], v[204:205], v[208:209]
	v_pk_fma_f32 v[218:219], v[198:199], v[224:225], v[220:221]
	v_pk_fma_f32 v[102:103], v[174:175], v[200:201], v[102:103]
	v_pk_mul_f32 v[218:219], v[110:111], v[218:219]
	v_pk_fma_f32 v[110:111], v[70:71], v[206:207], v[210:211]
	v_pk_fma_f32 v[64:65], v[196:197], v[64:65], v[102:103]
	v_pk_fma_f32 v[102:103], v[172:173], v[206:207], v[210:211]
	v_pk_fma_f32 v[110:111], v[184:185], v[202:203], v[110:111]
	v_pk_fma_f32 v[102:103], v[70:71], v[202:203], v[102:103]
	v_pk_fma_f32 v[78:79], v[198:199], v[78:79], v[110:111]
	v_pk_mul_f32 v[64:65], v[98:99], v[64:65]
	v_pk_fma_f32 v[98:99], v[74:75], v[204:205], v[208:209]
	v_pk_fma_f32 v[102:103], v[184:185], v[198:199], v[102:103]
	v_pk_mul_f32 v[78:79], v[106:107], v[78:79]
	v_pk_fma_f32 v[98:99], v[66:67], v[200:201], v[98:99]
	v_pk_mul_f32 v[220:221], v[222:223], v[102:103]
	v_pk_fma_f32 v[102:103], v[68:69], v[204:205], v[208:209]
	v_pk_fma_f32 v[106:107], v[72:73], v[206:207], v[210:211]
	v_pk_fma_f32 v[98:99], v[174:175], v[196:197], v[98:99]
	v_pk_fma_f32 v[106:107], v[172:173], v[202:203], v[106:107]
	v_pk_fma_f32 v[102:103], v[74:75], v[200:201], v[102:103]
	v_pk_mul_f32 v[98:99], v[212:213], v[98:99]
	v_pk_fma_f32 v[102:103], v[66:67], v[196:197], v[102:103]
	v_pk_fma_f32 v[106:107], v[70:71], v[198:199], v[106:107]
	v_pk_mul_f32 v[198:199], v[216:217], v[102:103]
	v_pk_mul_f32 v[196:197], v[214:215], v[106:107]
	v_cvt_pk_bf16_f32 v110, v76, v77
	v_cvt_pk_bf16_f32 v111, v218, v219
	v_cvt_pk_bf16_f32 v106, v64, v65
	v_cvt_pk_bf16_f32 v107, v78, v79
	v_cvt_pk_bf16_f32 v102, v98, v99
	v_cvt_pk_bf16_f32 v103, v220, v221
	v_cvt_pk_bf16_f32 v98, v198, v199
	s_nop 0
	v_cvt_pk_bf16_f32 v99, v196, v197
	v_lshlrev_b64 v[64:65], 1, v[158:159]
	s_and_saveexec_b64 s[8:9], s[0:1]
	s_cbranch_execz .LBB0_750
	v_mov_b64_e32 v[76:77], s[22:23]
	v_mad_i64_i32 v[78:79], s[10:11], v148, s56, v[76:77]
	v_mad_i64_i32 v[76:77], s[10:11], v150, s56, v[76:77]
	v_lshl_add_u64 v[78:79], v[78:79], 0, v[64:65]
	v_lshl_add_u64 v[76:77], v[76:77], 0, v[64:65]
	global_store_dwordx4 v[78:79], v[108:111], off
	global_store_dwordx4 v[76:77], v[104:107], off

; __global__ void __launch_bounds__(NT) mega(Args a) {
	.amdhsa_kernel _Z4mega4Args
		.amdhsa_group_segment_fixed_size 19456
		.amdhsa_private_segment_fixed_size 0
		.amdhsa_kernarg_size 416
		.amdhsa_user_sgpr_count 2
		.amdhsa_user_sgpr_dispatch_ptr 0
		.amdhsa_user_sgpr_queue_ptr 0
		.amdhsa_user_sgpr_kernarg_segment_ptr 1
		.amdhsa_user_sgpr_dispatch_id 0
		.amdhsa_user_sgpr_kernarg_preload_length 0
		.amdhsa_user_sgpr_kernarg_preload_offset 0
		.amdhsa_user_sgpr_private_segment_size 0
		.amdhsa_uses_dynamic_stack 0
		.amdhsa_enable_private_segment 0
		.amdhsa_system_sgpr_workgroup_id_x 1
		.amdhsa_system_sgpr_workgroup_id_y 0
		.amdhsa_system_sgpr_workgroup_id_z 0
		.amdhsa_system_sgpr_workgroup_info 0
		.amdhsa_system_vgpr_workitem_id 2
		.amdhsa_next_free_vgpr 256
		.amdhsa_next_free_sgpr 102
		.amdhsa_accum_offset 256
		.amdhsa_reserve_vcc 1
		.amdhsa_float_round_mode_32 0
		.amdhsa_float_round_mode_16_64 0
		.amdhsa_float_denorm_mode_32 3
		.amdhsa_float_denorm_mode_16_64 3
		.amdhsa_dx10_clamp 1
		.amdhsa_ieee_mode 1
		.amdhsa_fp16_overflow 0
		.amdhsa_tg_split 0
		.amdhsa_exception_fp_ieee_invalid_op 0
		.amdhsa_exception_fp_denorm_src 0
		.amdhsa_exception_fp_ieee_div_zero 0
		.amdhsa_exception_fp_ieee_overflow 0
		.amdhsa_exception_fp_ieee_underflow 0
		.amdhsa_exception_fp_ieee_inexact 0
		.amdhsa_exception_int_div_zero 0
	.end_amdhsa_kernel

; __global__ void __launch_bounds__(NT) mega(Args a) {
amdhsa.kernels:
  - .agpr_count:     0
    .args:
      - .offset:         0
        .size:           160
        .value_kind:     by_value
      - .offset:         160
        .size:           4
        .value_kind:     hidden_block_count_x
      - .offset:         164
        .size:           4
        .value_kind:     hidden_block_count_y
      - .offset:         168
        .size:           4
        .value_kind:     hidden_block_count_z
      - .offset:         172
        .size:           2
        .value_kind:     hidden_group_size_x
      - .offset:         174
        .size:           2
        .value_kind:     hidden_group_size_y
      - .offset:         176
        .size:           2
        .value_kind:     hidden_group_size_z
      - .offset:         178
        .size:           2
        .value_kind:     hidden_remainder_x
      - .offset:         180
        .size:           2
        .value_kind:     hidden_remainder_y
      - .offset:         182
        .size:           2
        .value_kind:     hidden_remainder_z
      - .offset:         200
        .size:           8
        .value_kind:     hidden_global_offset_x
      - .offset:         208
        .size:           8
        .value_kind:     hidden_global_offset_y
      - .offset:         216
        .size:           8
        .value_kind:     hidden_global_offset_z
      - .offset:         224
        .size:           2
        .value_kind:     hidden_grid_dims
      - .offset:         248
        .size:           8
        .value_kind:     hidden_multigrid_sync_arg
      - .offset:         280
        .size:           4
        .value_kind:     hidden_dynamic_lds_size
    .group_segment_fixed_size: 19456
    .kernarg_segment_align: 8
    .kernarg_segment_size: 416
    .language:       OpenCL C
    .language_version:
      - 2
      - 0
    .max_flat_workgroup_size: 512
    .name:           _Z4mega4Args
    .private_segment_fixed_size: 0
    .sgpr_count:     108
    .sgpr_spill_count: 98
    .symbol:         _Z4mega4Args.kd
    .uniform_work_group_size: 1
    .uses_dynamic_stack: false
    .vgpr_count:     256
    .vgpr_spill_count: 0
    .wavefront_size: 64
